# residual epilogues: permlane16_swap widens residual loads/stores to 16B, loads overlapped with lane exchange, counted waits
# speedup vs baseline: 1.0684x; 1.0367x over previous
;     __device__ __forceinline__ void operator()(const f32x4 (&acc)[2][2][4][2], const Unit& u, int wr, int wc, int fr, int fq) const {
;     ...
;         const int row0 = u.pm * BM + wr * 64 + fr, col0 = u.pn * BM + wc * 32 + 4 * fq;
;         u32x2v bs[2][4][2][2];
; #pragma unroll
;         for (int ai = 0; ai < 2; ++ai)
; #pragma unroll
;             for (int m = 0; m < 4; ++m)
; #pragma unroll
;                 for (int bj = 0; bj < 2; ++bj)
; #pragma unroll
;                     for (int n = 0; n < 2; ++n) bs[ai][m][bj][n] = *(const u32x2v*)(hb + (size_t)(row0 + ai * HALF + m * 16) * 1024 + col0 + bj * HALF + n * 16);
.LBB0_523:
	s_lshl_b32 s6, s24, 8
	s_add_i32 s6, s6, s16
	v_add_u32_e32 v136, s6, v228
	v_ashrrev_i32_e32 v137, 31, v136
	v_and_b32_e32 v139, 4, v230
	v_lshlrev_b32_e32 v139, 2, v139
	v_and_b32_e32 v138, 0x68, v230
	v_or_b32_e32 v138, v138, v139
	v_lshl_or_b32 v138, s23, 8, v138
	v_lshlrev_b32_e32 v138, 1, v138
	v_mov_b32_e32 v139, 0
	v_lshlrev_b64 v[140:141], 11, v[136:137]
	v_lshl_add_u64 v[140:141], s[84:85], 0, v[140:141]
	v_lshl_add_u64 v[212:213], v[140:141], 0, v[138:139]
	global_load_dwordx4 v[144:147], v[212:213], off
	global_load_dwordx4 v[148:151], v[212:213], off offset:256
	s_mov_b64 s[6:7], 0x8000
	v_lshl_add_u64 v[214:215], v[212:213], 0, s[6:7]
	global_load_dwordx4 v[152:155], v[214:215], off
	global_load_dwordx4 v[156:159], v[214:215], off offset:256
	s_mov_b64 s[6:7], 0x10000
	v_lshl_add_u64 v[216:217], v[212:213], 0, s[6:7]
	global_load_dwordx4 v[160:163], v[216:217], off
	global_load_dwordx4 v[168:171], v[216:217], off offset:256
	s_mov_b64 s[6:7], 0x18000
	v_lshl_add_u64 v[218:219], v[212:213], 0, s[6:7]
	global_load_dwordx4 v[172:175], v[218:219], off
	global_load_dwordx4 v[176:179], v[218:219], off offset:256
	s_mov_b64 s[6:7], 0x40000
	v_lshl_add_u64 v[220:221], v[212:213], 0, s[6:7]
	global_load_dwordx4 v[180:183], v[220:221], off
	global_load_dwordx4 v[184:187], v[220:221], off offset:256
	s_mov_b64 s[6:7], 0x48000
	v_lshl_add_u64 v[222:223], v[212:213], 0, s[6:7]
	global_load_dwordx4 v[188:191], v[222:223], off
	global_load_dwordx4 v[192:195], v[222:223], off offset:256
	s_mov_b64 s[6:7], 0x50000
	v_lshl_add_u64 v[224:225], v[212:213], 0, s[6:7]
	global_load_dwordx4 v[196:199], v[224:225], off
	global_load_dwordx4 v[200:203], v[224:225], off offset:256
	s_mov_b64 s[6:7], 0x58000
	v_lshl_add_u64 v[226:227], v[212:213], 0, s[6:7]
	global_load_dwordx4 v[204:207], v[226:227], off
	global_load_dwordx4 v[208:211], v[226:227], off offset:256
	v_permlane16_swap_b32_e32 v126, v122
	v_permlane16_swap_b32_e32 v127, v123
	v_permlane16_swap_b32_e32 v128, v124
	v_permlane16_swap_b32_e32 v129, v125
	v_permlane16_swap_b32_e32 v118, v114
	v_permlane16_swap_b32_e32 v119, v115
	v_permlane16_swap_b32_e32 v120, v116
	v_permlane16_swap_b32_e32 v121, v117
	v_permlane16_swap_b32_e32 v110, v106
	v_permlane16_swap_b32_e32 v111, v107
	v_permlane16_swap_b32_e32 v112, v108
	v_permlane16_swap_b32_e32 v113, v109
	v_permlane16_swap_b32_e32 v102, v98
	v_permlane16_swap_b32_e32 v103, v99
	v_permlane16_swap_b32_e32 v104, v100
	v_permlane16_swap_b32_e32 v105, v101
	v_permlane16_swap_b32_e32 v94, v90
	v_permlane16_swap_b32_e32 v95, v91
	v_permlane16_swap_b32_e32 v96, v92
	v_permlane16_swap_b32_e32 v97, v93
	v_permlane16_swap_b32_e32 v86, v82
	v_permlane16_swap_b32_e32 v87, v83
	v_permlane16_swap_b32_e32 v88, v84
	v_permlane16_swap_b32_e32 v89, v85
	v_permlane16_swap_b32_e32 v78, v74
	v_permlane16_swap_b32_e32 v79, v75
	v_permlane16_swap_b32_e32 v80, v76
	v_permlane16_swap_b32_e32 v81, v77
	v_permlane16_swap_b32_e32 v70, v66
	v_permlane16_swap_b32_e32 v71, v67
	v_permlane16_swap_b32_e32 v72, v68
	v_permlane16_swap_b32_e32 v73, v69
	v_permlane16_swap_b32_e32 v62, v58
	v_permlane16_swap_b32_e32 v63, v59
	v_permlane16_swap_b32_e32 v64, v60
	v_permlane16_swap_b32_e32 v65, v61
	v_permlane16_swap_b32_e32 v54, v50
	v_permlane16_swap_b32_e32 v55, v51
	v_permlane16_swap_b32_e32 v56, v52
	v_permlane16_swap_b32_e32 v57, v53
	v_permlane16_swap_b32_e32 v46, v42
	v_permlane16_swap_b32_e32 v47, v43
	v_permlane16_swap_b32_e32 v48, v44
	v_permlane16_swap_b32_e32 v49, v45
	v_permlane16_swap_b32_e32 v38, v34
	v_permlane16_swap_b32_e32 v39, v35
	v_permlane16_swap_b32_e32 v40, v36
	v_permlane16_swap_b32_e32 v41, v37
	v_permlane16_swap_b32_e32 v30, v26
	v_permlane16_swap_b32_e32 v31, v27
	v_permlane16_swap_b32_e32 v32, v28
	v_permlane16_swap_b32_e32 v33, v29
	v_permlane16_swap_b32_e32 v22, v18
	v_permlane16_swap_b32_e32 v23, v19
	v_permlane16_swap_b32_e32 v24, v20
	v_permlane16_swap_b32_e32 v25, v21
	v_permlane16_swap_b32_e32 v14, v10
	v_permlane16_swap_b32_e32 v15, v11
	v_permlane16_swap_b32_e32 v16, v12
	v_permlane16_swap_b32_e32 v17, v13
	v_permlane16_swap_b32_e32 v6, v2
	v_permlane16_swap_b32_e32 v7, v3
	v_permlane16_swap_b32_e32 v8, v4
	v_permlane16_swap_b32_e32 v9, v5
	v_xor_b32_e32 v232, 16, v242
	v_lshlrev_b32_e32 v232, 2, v232
	v_xor_b32_e32 v233, 32, v242
	v_lshlrev_b32_e32 v233, 2, v233
	s_waitcnt vmcnt(15)
	v_lshlrev_b32_e32 v140, 16, v144
	v_and_b32_e32 v141, 0xffff0000, v144
	v_lshlrev_b32_e32 v142, 16, v145
	v_and_b32_e32 v143, 0xffff0000, v145
	v_pk_add_f32 v[126:127], v[126:127], v[140:141]
	v_pk_add_f32 v[128:129], v[128:129], v[142:143]
	v_lshlrev_b32_e32 v140, 16, v146
	v_and_b32_e32 v141, 0xffff0000, v146
	v_lshlrev_b32_e32 v142, 16, v147
	v_and_b32_e32 v143, 0xffff0000, v147
	v_pk_add_f32 v[122:123], v[122:123], v[140:141]
	v_pk_add_f32 v[124:125], v[124:125], v[142:143]
	v_cvt_pk_bf16_f32 v144, v126, v127
	v_cvt_pk_bf16_f32 v145, v128, v129
	v_cvt_pk_bf16_f32 v146, v122, v123
	v_cvt_pk_bf16_f32 v147, v124, v125
	global_store_dwordx4 v[212:213], v[144:147], off
	v_mul_f32_e32 v140, v126, v126
	v_mul_f32_e32 v141, v122, v122
	v_fmac_f32_e32 v140, v127, v127
	v_fmac_f32_e32 v141, v123, v123
	v_fmac_f32_e32 v140, v128, v128
	v_fmac_f32_e32 v141, v124, v124
	v_fmac_f32_e32 v140, v129, v129
	v_fmac_f32_e32 v141, v125, v125
	v_add_f32_e32 v138, v140, v141
	s_waitcnt vmcnt(15)
; __device__ __forceinline__ unsigned cvt_pk_bf16(float lo, float hi) { f32x2_t v = {lo, hi}; bf16x2_t b = __builtin_convertvector(v, bf16x2_t); return __builtin_bit_cast(unsigned, b); }
;     __device__ __forceinline__ void operator()(const f32x4 (&acc)[2][2][4][2], const Unit& u, int wr, int wc, int fr, int fq) const {
;     ...
;             for (int m = 0; m < 4; ++m) { const int row = row0 + ai * HALF + m * 16; const size_t off = (size_t)row * 1024 + col0; float q = 0.f;
; #pragma unroll
;                 for (int bj = 0; bj < 2; ++bj)
; #pragma unroll
;                     for (int n = 0; n < 2; ++n) { const size_t o2 = off + bj * HALF + n * 16; const u32x2v b = bs[ai][m][bj][n];
;                         const f32x4 bf = {__builtin_bit_cast(float, b.x << 16), __builtin_bit_cast(float, b.x & 0xffff0000u), __builtin_bit_cast(float, b.y << 16), __builtin_bit_cast(float, b.y & 0xffff0000u)};
;                         const f32x4 o = bf + acc[ai][bj][m][n];
;                         u32x2v w; w.x = cvt_pk_bf16(o[0], o[1]); w.y = cvt_pk_bf16(o[2], o[3]); *(u32x2v*)(hb + o2) = w;
;                         q += (o[0] * o[0] + o[1] * o[1]) + (o[2] * o[2] + o[3] * o[3]); }
	v_lshlrev_b32_e32 v140, 16, v148
	v_and_b32_e32 v141, 0xffff0000, v148
	v_lshlrev_b32_e32 v142, 16, v149
	v_and_b32_e32 v143, 0xffff0000, v149
	v_pk_add_f32 v[118:119], v[118:119], v[140:141]
	v_pk_add_f32 v[120:121], v[120:121], v[142:143]
	v_lshlrev_b32_e32 v140, 16, v150
	v_and_b32_e32 v141, 0xffff0000, v150
	v_lshlrev_b32_e32 v142, 16, v151
	v_and_b32_e32 v143, 0xffff0000, v151
	v_pk_add_f32 v[114:115], v[114:115], v[140:141]
	v_pk_add_f32 v[116:117], v[116:117], v[142:143]
	v_cvt_pk_bf16_f32 v148, v118, v119
	v_cvt_pk_bf16_f32 v149, v120, v121
	v_cvt_pk_bf16_f32 v150, v114, v115
	v_cvt_pk_bf16_f32 v151, v116, v117
	global_store_dwordx4 v[212:213], v[148:151], off offset:256
	v_mul_f32_e32 v140, v118, v118
	v_mul_f32_e32 v141, v114, v114
	v_fmac_f32_e32 v140, v119, v119
	v_fmac_f32_e32 v141, v115, v115
	v_fmac_f32_e32 v140, v120, v120
	v_fmac_f32_e32 v141, v116, v116
	v_fmac_f32_e32 v140, v121, v121
	v_fmac_f32_e32 v141, v117, v117
	v_add_f32_e32 v139, v140, v141
	v_add_f32_e32 v212, v138, v139
	s_waitcnt vmcnt(15)
	v_lshlrev_b32_e32 v140, 16, v152
	v_and_b32_e32 v141, 0xffff0000, v152
	v_lshlrev_b32_e32 v142, 16, v153
	v_and_b32_e32 v143, 0xffff0000, v153
	v_pk_add_f32 v[110:111], v[110:111], v[140:141]
	v_pk_add_f32 v[112:113], v[112:113], v[142:143]
	v_lshlrev_b32_e32 v140, 16, v154
	v_and_b32_e32 v141, 0xffff0000, v154
	v_lshlrev_b32_e32 v142, 16, v155
	v_and_b32_e32 v143, 0xffff0000, v155
	v_pk_add_f32 v[106:107], v[106:107], v[140:141]
	v_pk_add_f32 v[108:109], v[108:109], v[142:143]
	v_cvt_pk_bf16_f32 v152, v110, v111
	v_cvt_pk_bf16_f32 v153, v112, v113
	v_cvt_pk_bf16_f32 v154, v106, v107
	v_cvt_pk_bf16_f32 v155, v108, v109
	global_store_dwordx4 v[214:215], v[152:155], off
	v_mul_f32_e32 v140, v110, v110
	v_mul_f32_e32 v141, v106, v106
	v_fmac_f32_e32 v140, v111, v111
	v_fmac_f32_e32 v141, v107, v107
	v_fmac_f32_e32 v140, v112, v112
	v_fmac_f32_e32 v141, v108, v108
	v_fmac_f32_e32 v140, v113, v113
	v_fmac_f32_e32 v141, v109, v109
	v_add_f32_e32 v138, v140, v141
	s_waitcnt vmcnt(15)
	v_lshlrev_b32_e32 v140, 16, v156
	v_and_b32_e32 v141, 0xffff0000, v156
	v_lshlrev_b32_e32 v142, 16, v157
	v_and_b32_e32 v143, 0xffff0000, v157
	v_pk_add_f32 v[102:103], v[102:103], v[140:141]
	v_pk_add_f32 v[104:105], v[104:105], v[142:143]
	v_lshlrev_b32_e32 v140, 16, v158
	v_and_b32_e32 v141, 0xffff0000, v158
	v_lshlrev_b32_e32 v142, 16, v159
	v_and_b32_e32 v143, 0xffff0000, v159
	v_pk_add_f32 v[98:99], v[98:99], v[140:141]
	v_pk_add_f32 v[100:101], v[100:101], v[142:143]
	v_cvt_pk_bf16_f32 v156, v102, v103
	v_cvt_pk_bf16_f32 v157, v104, v105
	v_cvt_pk_bf16_f32 v158, v98, v99
	v_cvt_pk_bf16_f32 v159, v100, v101
	global_store_dwordx4 v[214:215], v[156:159], off offset:256
	v_mul_f32_e32 v140, v102, v102
	v_mul_f32_e32 v141, v98, v98
	v_fmac_f32_e32 v140, v103, v103
	v_fmac_f32_e32 v141, v99, v99
	v_fmac_f32_e32 v140, v104, v104
	v_fmac_f32_e32 v141, v100, v100
	v_fmac_f32_e32 v140, v105, v105
	v_fmac_f32_e32 v141, v101, v101
	v_add_f32_e32 v139, v140, v141
	v_add_f32_e32 v214, v138, v139
	s_waitcnt vmcnt(15)
	v_lshlrev_b32_e32 v140, 16, v160
	v_and_b32_e32 v141, 0xffff0000, v160
	v_lshlrev_b32_e32 v142, 16, v161
	v_and_b32_e32 v143, 0xffff0000, v161
	v_pk_add_f32 v[94:95], v[94:95], v[140:141]
	v_pk_add_f32 v[96:97], v[96:97], v[142:143]
	v_lshlrev_b32_e32 v140, 16, v162
	v_and_b32_e32 v141, 0xffff0000, v162
	v_lshlrev_b32_e32 v142, 16, v163
	v_and_b32_e32 v143, 0xffff0000, v163
	v_pk_add_f32 v[90:91], v[90:91], v[140:141]
	v_pk_add_f32 v[92:93], v[92:93], v[142:143]
	v_cvt_pk_bf16_f32 v160, v94, v95
	v_cvt_pk_bf16_f32 v161, v96, v97
	v_cvt_pk_bf16_f32 v162, v90, v91
	v_cvt_pk_bf16_f32 v163, v92, v93
	global_store_dwordx4 v[216:217], v[160:163], off
	v_mul_f32_e32 v140, v94, v94
	v_mul_f32_e32 v141, v90, v90
	v_fmac_f32_e32 v140, v95, v95
	v_fmac_f32_e32 v141, v91, v91
	v_fmac_f32_e32 v140, v96, v96
	v_fmac_f32_e32 v141, v92, v92
	v_fmac_f32_e32 v140, v97, v97
	v_fmac_f32_e32 v141, v93, v93
	v_add_f32_e32 v138, v140, v141
	s_waitcnt vmcnt(15)
	v_lshlrev_b32_e32 v140, 16, v168
	v_and_b32_e32 v141, 0xffff0000, v168
	v_lshlrev_b32_e32 v142, 16, v169
	v_and_b32_e32 v143, 0xffff0000, v169
	v_pk_add_f32 v[86:87], v[86:87], v[140:141]
	v_pk_add_f32 v[88:89], v[88:89], v[142:143]
	v_lshlrev_b32_e32 v140, 16, v170
	v_and_b32_e32 v141, 0xffff0000, v170
	v_lshlrev_b32_e32 v142, 16, v171
	v_and_b32_e32 v143, 0xffff0000, v171
	v_pk_add_f32 v[82:83], v[82:83], v[140:141]
	v_pk_add_f32 v[84:85], v[84:85], v[142:143]
	v_cvt_pk_bf16_f32 v168, v86, v87
	v_cvt_pk_bf16_f32 v169, v88, v89
	v_cvt_pk_bf16_f32 v170, v82, v83
	v_cvt_pk_bf16_f32 v171, v84, v85
	global_store_dwordx4 v[216:217], v[168:171], off offset:256
	v_mul_f32_e32 v140, v86, v86
	v_mul_f32_e32 v141, v82, v82
	v_fmac_f32_e32 v140, v87, v87
	v_fmac_f32_e32 v141, v83, v83
	v_fmac_f32_e32 v140, v88, v88
	v_fmac_f32_e32 v141, v84, v84
	v_fmac_f32_e32 v140, v89, v89
	v_fmac_f32_e32 v141, v85, v85
	v_add_f32_e32 v139, v140, v141
	v_add_f32_e32 v216, v138, v139
	s_waitcnt vmcnt(15)
	v_lshlrev_b32_e32 v140, 16, v172
	v_and_b32_e32 v141, 0xffff0000, v172
	v_lshlrev_b32_e32 v142, 16, v173
	v_and_b32_e32 v143, 0xffff0000, v173
	v_pk_add_f32 v[78:79], v[78:79], v[140:141]
	v_pk_add_f32 v[80:81], v[80:81], v[142:143]
	v_lshlrev_b32_e32 v140, 16, v174
	v_and_b32_e32 v141, 0xffff0000, v174
	v_lshlrev_b32_e32 v142, 16, v175
	v_and_b32_e32 v143, 0xffff0000, v175
	v_pk_add_f32 v[74:75], v[74:75], v[140:141]
	v_pk_add_f32 v[76:77], v[76:77], v[142:143]
	v_cvt_pk_bf16_f32 v172, v78, v79
	v_cvt_pk_bf16_f32 v173, v80, v81
	v_cvt_pk_bf16_f32 v174, v74, v75
	v_cvt_pk_bf16_f32 v175, v76, v77
	global_store_dwordx4 v[218:219], v[172:175], off
	v_mul_f32_e32 v140, v78, v78
	v_mul_f32_e32 v141, v74, v74
	v_fmac_f32_e32 v140, v79, v79
	v_fmac_f32_e32 v141, v75, v75
	v_fmac_f32_e32 v140, v80, v80
	v_fmac_f32_e32 v141, v76, v76
	v_fmac_f32_e32 v140, v81, v81
	v_fmac_f32_e32 v141, v77, v77
	v_add_f32_e32 v138, v140, v141
	s_waitcnt vmcnt(15)
; __device__ __forceinline__ unsigned cvt_pk_bf16(float lo, float hi) { f32x2_t v = {lo, hi}; bf16x2_t b = __builtin_convertvector(v, bf16x2_t); return __builtin_bit_cast(unsigned, b); }
;     __device__ __forceinline__ void operator()(const f32x4 (&acc)[2][2][4][2], const Unit& u, int wr, int wc, int fr, int fq) const {
;     ...
;             for (int m = 0; m < 4; ++m) { const int row = row0 + ai * HALF + m * 16; const size_t off = (size_t)row * 1024 + col0; float q = 0.f;
; #pragma unroll
;                 for (int bj = 0; bj < 2; ++bj)
; #pragma unroll
;                     for (int n = 0; n < 2; ++n) { const size_t o2 = off + bj * HALF + n * 16; const u32x2v b = bs[ai][m][bj][n];
;                         const f32x4 bf = {__builtin_bit_cast(float, b.x << 16), __builtin_bit_cast(float, b.x & 0xffff0000u), __builtin_bit_cast(float, b.y << 16), __builtin_bit_cast(float, b.y & 0xffff0000u)};
;                         const f32x4 o = bf + acc[ai][bj][m][n];
;                         u32x2v w; w.x = cvt_pk_bf16(o[0], o[1]); w.y = cvt_pk_bf16(o[2], o[3]); *(u32x2v*)(hb + o2) = w;
;                         q += (o[0] * o[0] + o[1] * o[1]) + (o[2] * o[2] + o[3] * o[3]); }
	v_lshlrev_b32_e32 v140, 16, v176
	v_and_b32_e32 v141, 0xffff0000, v176
	v_lshlrev_b32_e32 v142, 16, v177
	v_and_b32_e32 v143, 0xffff0000, v177
	v_pk_add_f32 v[70:71], v[70:71], v[140:141]
	v_pk_add_f32 v[72:73], v[72:73], v[142:143]
	v_lshlrev_b32_e32 v140, 16, v178
	v_and_b32_e32 v141, 0xffff0000, v178
	v_lshlrev_b32_e32 v142, 16, v179
	v_and_b32_e32 v143, 0xffff0000, v179
	v_pk_add_f32 v[66:67], v[66:67], v[140:141]
	v_pk_add_f32 v[68:69], v[68:69], v[142:143]
	v_cvt_pk_bf16_f32 v176, v70, v71
	v_cvt_pk_bf16_f32 v177, v72, v73
	v_cvt_pk_bf16_f32 v178, v66, v67
	v_cvt_pk_bf16_f32 v179, v68, v69
	global_store_dwordx4 v[218:219], v[176:179], off offset:256
	v_mul_f32_e32 v140, v70, v70
	v_mul_f32_e32 v141, v66, v66
	v_fmac_f32_e32 v140, v71, v71
	v_fmac_f32_e32 v141, v67, v67
	v_fmac_f32_e32 v140, v72, v72
	v_fmac_f32_e32 v141, v68, v68
	v_fmac_f32_e32 v140, v73, v73
	v_fmac_f32_e32 v141, v69, v69
	v_add_f32_e32 v139, v140, v141
	v_add_f32_e32 v218, v138, v139
	s_waitcnt vmcnt(15)
	v_lshlrev_b32_e32 v140, 16, v180
	v_and_b32_e32 v141, 0xffff0000, v180
	v_lshlrev_b32_e32 v142, 16, v181
	v_and_b32_e32 v143, 0xffff0000, v181
	v_pk_add_f32 v[62:63], v[62:63], v[140:141]
	v_pk_add_f32 v[64:65], v[64:65], v[142:143]
	v_lshlrev_b32_e32 v140, 16, v182
	v_and_b32_e32 v141, 0xffff0000, v182
	v_lshlrev_b32_e32 v142, 16, v183
	v_and_b32_e32 v143, 0xffff0000, v183
	v_pk_add_f32 v[58:59], v[58:59], v[140:141]
	v_pk_add_f32 v[60:61], v[60:61], v[142:143]
	v_cvt_pk_bf16_f32 v180, v62, v63
	v_cvt_pk_bf16_f32 v181, v64, v65
	v_cvt_pk_bf16_f32 v182, v58, v59
	v_cvt_pk_bf16_f32 v183, v60, v61
	global_store_dwordx4 v[220:221], v[180:183], off
	v_mul_f32_e32 v140, v62, v62
	v_mul_f32_e32 v141, v58, v58
	v_fmac_f32_e32 v140, v63, v63
	v_fmac_f32_e32 v141, v59, v59
	v_fmac_f32_e32 v140, v64, v64
	v_fmac_f32_e32 v141, v60, v60
	v_fmac_f32_e32 v140, v65, v65
	v_fmac_f32_e32 v141, v61, v61
	v_add_f32_e32 v138, v140, v141
	s_waitcnt vmcnt(15)
	v_lshlrev_b32_e32 v140, 16, v184
	v_and_b32_e32 v141, 0xffff0000, v184
	v_lshlrev_b32_e32 v142, 16, v185
	v_and_b32_e32 v143, 0xffff0000, v185
	v_pk_add_f32 v[54:55], v[54:55], v[140:141]
	v_pk_add_f32 v[56:57], v[56:57], v[142:143]
	v_lshlrev_b32_e32 v140, 16, v186
	v_and_b32_e32 v141, 0xffff0000, v186
	v_lshlrev_b32_e32 v142, 16, v187
	v_and_b32_e32 v143, 0xffff0000, v187
	v_pk_add_f32 v[50:51], v[50:51], v[140:141]
	v_pk_add_f32 v[52:53], v[52:53], v[142:143]
	v_cvt_pk_bf16_f32 v184, v54, v55
	v_cvt_pk_bf16_f32 v185, v56, v57
	v_cvt_pk_bf16_f32 v186, v50, v51
	v_cvt_pk_bf16_f32 v187, v52, v53
	global_store_dwordx4 v[220:221], v[184:187], off offset:256
	v_mul_f32_e32 v140, v54, v54
	v_mul_f32_e32 v141, v50, v50
	v_fmac_f32_e32 v140, v55, v55
	v_fmac_f32_e32 v141, v51, v51
	v_fmac_f32_e32 v140, v56, v56
	v_fmac_f32_e32 v141, v52, v52
	v_fmac_f32_e32 v140, v57, v57
	v_fmac_f32_e32 v141, v53, v53
	v_add_f32_e32 v139, v140, v141
	v_add_f32_e32 v220, v138, v139
	s_waitcnt vmcnt(15)
	v_lshlrev_b32_e32 v140, 16, v188
	v_and_b32_e32 v141, 0xffff0000, v188
	v_lshlrev_b32_e32 v142, 16, v189
	v_and_b32_e32 v143, 0xffff0000, v189
	v_pk_add_f32 v[46:47], v[46:47], v[140:141]
	v_pk_add_f32 v[48:49], v[48:49], v[142:143]
	v_lshlrev_b32_e32 v140, 16, v190
	v_and_b32_e32 v141, 0xffff0000, v190
	v_lshlrev_b32_e32 v142, 16, v191
	v_and_b32_e32 v143, 0xffff0000, v191
	v_pk_add_f32 v[42:43], v[42:43], v[140:141]
	v_pk_add_f32 v[44:45], v[44:45], v[142:143]
	v_cvt_pk_bf16_f32 v188, v46, v47
	v_cvt_pk_bf16_f32 v189, v48, v49
	v_cvt_pk_bf16_f32 v190, v42, v43
	v_cvt_pk_bf16_f32 v191, v44, v45
	global_store_dwordx4 v[222:223], v[188:191], off
	v_mul_f32_e32 v140, v46, v46
	v_mul_f32_e32 v141, v42, v42
	v_fmac_f32_e32 v140, v47, v47
	v_fmac_f32_e32 v141, v43, v43
	v_fmac_f32_e32 v140, v48, v48
	v_fmac_f32_e32 v141, v44, v44
	v_fmac_f32_e32 v140, v49, v49
	v_fmac_f32_e32 v141, v45, v45
	v_add_f32_e32 v138, v140, v141
	s_waitcnt vmcnt(15)
	v_lshlrev_b32_e32 v140, 16, v192
	v_and_b32_e32 v141, 0xffff0000, v192
	v_lshlrev_b32_e32 v142, 16, v193
	v_and_b32_e32 v143, 0xffff0000, v193
	v_pk_add_f32 v[38:39], v[38:39], v[140:141]
	v_pk_add_f32 v[40:41], v[40:41], v[142:143]
	v_lshlrev_b32_e32 v140, 16, v194
	v_and_b32_e32 v141, 0xffff0000, v194
	v_lshlrev_b32_e32 v142, 16, v195
	v_and_b32_e32 v143, 0xffff0000, v195
	v_pk_add_f32 v[34:35], v[34:35], v[140:141]
	v_pk_add_f32 v[36:37], v[36:37], v[142:143]
	v_cvt_pk_bf16_f32 v192, v38, v39
	v_cvt_pk_bf16_f32 v193, v40, v41
	v_cvt_pk_bf16_f32 v194, v34, v35
	v_cvt_pk_bf16_f32 v195, v36, v37
	global_store_dwordx4 v[222:223], v[192:195], off offset:256
	v_mul_f32_e32 v140, v38, v38
	v_mul_f32_e32 v141, v34, v34
	v_fmac_f32_e32 v140, v39, v39
	v_fmac_f32_e32 v141, v35, v35
	v_fmac_f32_e32 v140, v40, v40
	v_fmac_f32_e32 v141, v36, v36
	v_fmac_f32_e32 v140, v41, v41
	v_fmac_f32_e32 v141, v37, v37
	v_add_f32_e32 v139, v140, v141
	v_add_f32_e32 v222, v138, v139
	s_waitcnt vmcnt(15)
; __device__ __forceinline__ unsigned cvt_pk_bf16(float lo, float hi) { f32x2_t v = {lo, hi}; bf16x2_t b = __builtin_convertvector(v, bf16x2_t); return __builtin_bit_cast(unsigned, b); }
;     __device__ __forceinline__ void operator()(const f32x4 (&acc)[2][2][4][2], const Unit& u, int wr, int wc, int fr, int fq) const {
;     ...
;                     for (int n = 0; n < 2; ++n) { const size_t o2 = off + bj * HALF + n * 16; const u32x2v b = bs[ai][m][bj][n];
;                         const f32x4 bf = {__builtin_bit_cast(float, b.x << 16), __builtin_bit_cast(float, b.x & 0xffff0000u), __builtin_bit_cast(float, b.y << 16), __builtin_bit_cast(float, b.y & 0xffff0000u)};
;                         const f32x4 o = bf + acc[ai][bj][m][n];
;                         u32x2v w; w.x = cvt_pk_bf16(o[0], o[1]); w.y = cvt_pk_bf16(o[2], o[3]); *(u32x2v*)(hb + o2) = w;
;                         q += (o[0] * o[0] + o[1] * o[1]) + (o[2] * o[2] + o[3] * o[3]); }
;                 q += __shfl_xor(q, 16); q += __shfl_xor(q, 32);
;                 if (fq == 0) ssq[(size_t)(4 * u.pn + wc) * 16384 + row] = q; }
	v_lshlrev_b32_e32 v140, 16, v196
	v_and_b32_e32 v141, 0xffff0000, v196
	v_lshlrev_b32_e32 v142, 16, v197
	v_and_b32_e32 v143, 0xffff0000, v197
	v_pk_add_f32 v[30:31], v[30:31], v[140:141]
	v_pk_add_f32 v[32:33], v[32:33], v[142:143]
	v_lshlrev_b32_e32 v140, 16, v198
	v_and_b32_e32 v141, 0xffff0000, v198
	v_lshlrev_b32_e32 v142, 16, v199
	v_and_b32_e32 v143, 0xffff0000, v199
	v_pk_add_f32 v[26:27], v[26:27], v[140:141]
	v_pk_add_f32 v[28:29], v[28:29], v[142:143]
	v_cvt_pk_bf16_f32 v196, v30, v31
	v_cvt_pk_bf16_f32 v197, v32, v33
	v_cvt_pk_bf16_f32 v198, v26, v27
	v_cvt_pk_bf16_f32 v199, v28, v29
	global_store_dwordx4 v[224:225], v[196:199], off
	v_mul_f32_e32 v140, v30, v30
	v_mul_f32_e32 v141, v26, v26
	v_fmac_f32_e32 v140, v31, v31
	v_fmac_f32_e32 v141, v27, v27
	v_fmac_f32_e32 v140, v32, v32
	v_fmac_f32_e32 v141, v28, v28
	v_fmac_f32_e32 v140, v33, v33
	v_fmac_f32_e32 v141, v29, v29
	v_add_f32_e32 v138, v140, v141
	s_waitcnt vmcnt(15)
	v_lshlrev_b32_e32 v140, 16, v200
	v_and_b32_e32 v141, 0xffff0000, v200
	v_lshlrev_b32_e32 v142, 16, v201
	v_and_b32_e32 v143, 0xffff0000, v201
	v_pk_add_f32 v[22:23], v[22:23], v[140:141]
	v_pk_add_f32 v[24:25], v[24:25], v[142:143]
	v_lshlrev_b32_e32 v140, 16, v202
	v_and_b32_e32 v141, 0xffff0000, v202
	v_lshlrev_b32_e32 v142, 16, v203
	v_and_b32_e32 v143, 0xffff0000, v203
	v_pk_add_f32 v[18:19], v[18:19], v[140:141]
	v_pk_add_f32 v[20:21], v[20:21], v[142:143]
	v_cvt_pk_bf16_f32 v200, v22, v23
	v_cvt_pk_bf16_f32 v201, v24, v25
	v_cvt_pk_bf16_f32 v202, v18, v19
	v_cvt_pk_bf16_f32 v203, v20, v21
	global_store_dwordx4 v[224:225], v[200:203], off offset:256
	v_mul_f32_e32 v140, v22, v22
	v_mul_f32_e32 v141, v18, v18
	v_fmac_f32_e32 v140, v23, v23
	v_fmac_f32_e32 v141, v19, v19
	v_fmac_f32_e32 v140, v24, v24
	v_fmac_f32_e32 v141, v20, v20
	v_fmac_f32_e32 v140, v25, v25
	v_fmac_f32_e32 v141, v21, v21
	v_add_f32_e32 v139, v140, v141
	v_add_f32_e32 v224, v138, v139
	s_waitcnt vmcnt(15)
	v_lshlrev_b32_e32 v140, 16, v204
	v_and_b32_e32 v141, 0xffff0000, v204
	v_lshlrev_b32_e32 v142, 16, v205
	v_and_b32_e32 v143, 0xffff0000, v205
	v_pk_add_f32 v[14:15], v[14:15], v[140:141]
	v_pk_add_f32 v[16:17], v[16:17], v[142:143]
	v_lshlrev_b32_e32 v140, 16, v206
	v_and_b32_e32 v141, 0xffff0000, v206
	v_lshlrev_b32_e32 v142, 16, v207
	v_and_b32_e32 v143, 0xffff0000, v207
	v_pk_add_f32 v[10:11], v[10:11], v[140:141]
	v_pk_add_f32 v[12:13], v[12:13], v[142:143]
	v_cvt_pk_bf16_f32 v204, v14, v15
	v_cvt_pk_bf16_f32 v205, v16, v17
	v_cvt_pk_bf16_f32 v206, v10, v11
	v_cvt_pk_bf16_f32 v207, v12, v13
	global_store_dwordx4 v[226:227], v[204:207], off
	v_mul_f32_e32 v140, v14, v14
	v_mul_f32_e32 v141, v10, v10
	v_fmac_f32_e32 v140, v15, v15
	v_fmac_f32_e32 v141, v11, v11
	v_fmac_f32_e32 v140, v16, v16
	v_fmac_f32_e32 v141, v12, v12
	v_fmac_f32_e32 v140, v17, v17
	v_fmac_f32_e32 v141, v13, v13
	v_add_f32_e32 v138, v140, v141
	s_waitcnt vmcnt(15)
	v_lshlrev_b32_e32 v140, 16, v208
	v_and_b32_e32 v141, 0xffff0000, v208
	v_lshlrev_b32_e32 v142, 16, v209
	v_and_b32_e32 v143, 0xffff0000, v209
	v_pk_add_f32 v[6:7], v[6:7], v[140:141]
	v_pk_add_f32 v[8:9], v[8:9], v[142:143]
	v_lshlrev_b32_e32 v140, 16, v210
	v_and_b32_e32 v141, 0xffff0000, v210
	v_lshlrev_b32_e32 v142, 16, v211
	v_and_b32_e32 v143, 0xffff0000, v211
	v_pk_add_f32 v[2:3], v[2:3], v[140:141]
	v_pk_add_f32 v[4:5], v[4:5], v[142:143]
	v_cvt_pk_bf16_f32 v208, v6, v7
	v_cvt_pk_bf16_f32 v209, v8, v9
	v_cvt_pk_bf16_f32 v210, v2, v3
	v_cvt_pk_bf16_f32 v211, v4, v5
	global_store_dwordx4 v[226:227], v[208:211], off offset:256
	v_mul_f32_e32 v140, v6, v6
	v_mul_f32_e32 v141, v2, v2
	v_fmac_f32_e32 v140, v7, v7
	v_fmac_f32_e32 v141, v3, v3
	v_fmac_f32_e32 v140, v8, v8
	v_fmac_f32_e32 v141, v4, v4
	v_fmac_f32_e32 v140, v9, v9
	v_fmac_f32_e32 v141, v5, v5
	v_add_f32_e32 v139, v140, v141
	v_add_f32_e32 v226, v138, v139
	ds_bpermute_b32 v213, v232, v212
	ds_bpermute_b32 v215, v232, v214
	ds_bpermute_b32 v217, v232, v216
	ds_bpermute_b32 v219, v232, v218
	ds_bpermute_b32 v221, v232, v220
	ds_bpermute_b32 v223, v232, v222
	ds_bpermute_b32 v225, v232, v224
	ds_bpermute_b32 v227, v232, v226
	s_waitcnt lgkmcnt(0)
	v_add_f32_e32 v212, v212, v213
	v_add_f32_e32 v214, v214, v215
	v_add_f32_e32 v216, v216, v217
	v_add_f32_e32 v218, v218, v219
	v_add_f32_e32 v220, v220, v221
	v_add_f32_e32 v222, v222, v223
	v_add_f32_e32 v224, v224, v225
	v_add_f32_e32 v226, v226, v227
	ds_bpermute_b32 v213, v233, v212
	ds_bpermute_b32 v215, v233, v214
	ds_bpermute_b32 v217, v233, v216
	ds_bpermute_b32 v219, v233, v218
	ds_bpermute_b32 v221, v233, v220
	ds_bpermute_b32 v223, v233, v222
	ds_bpermute_b32 v225, v233, v224
	ds_bpermute_b32 v227, v233, v226
	s_waitcnt lgkmcnt(0)
	v_add_f32_e32 v212, v212, v213
	v_add_f32_e32 v214, v214, v215
	v_add_f32_e32 v216, v216, v217
	v_add_f32_e32 v218, v218, v219
	v_add_f32_e32 v220, v220, v221
	v_add_f32_e32 v222, v222, v223
	v_add_f32_e32 v224, v224, v225
	v_add_f32_e32 v226, v226, v227
	s_lshl_b32 s6, s23, 2
	s_or_b32 s6, s6, s12
	s_ashr_i32 s7, s6, 31
	s_lshl_b64 s[6:7], s[6:7], 16
	v_readlane_b32 s10, v252, 15
	v_readlane_b32 s11, v252, 16
	s_add_u32 s10, s10, s6
	s_addc_u32 s11, s11, s7
	v_lshl_add_u64 v[140:141], v[136:137], 2, s[10:11]
	s_and_saveexec_b64 s[8:9], s[38:39]
	global_store_dword v[140:141], v212, off
	global_store_dword v[140:141], v214, off offset:64
	global_store_dword v[140:141], v216, off offset:128
	global_store_dword v[140:141], v218, off offset:192
	global_store_dword v[140:141], v220, off offset:512
	global_store_dword v[140:141], v222, off offset:576
	global_store_dword v[140:141], v224, off offset:640
	global_store_dword v[140:141], v226, off offset:704
